# even scans: HGRN2 first half-interval: stage2 interleaved with the MFMA compute (subset of previous attempt)
# speedup vs baseline: 1.0042x; 1.0031x over previous
; template <int MODE>
; __device__ void scan_unit(int swave, const Params& p, int j, int b, int h, int dir, char* shm) {
;     ...
;   auto compute = [&](const char* buf, bf16_t* obuf) {
;     const bf16_t* qin = (const bf16_t*)buf; const bf16_t* ktil = (const bf16_t*)(buf + OFF_KT); const bf16_t* koutT = (const bf16_t*)(buf + OFF_KO);
;     const bf16_t* vT = (const bf16_t*)(buf + OFF_VT); const float* dec = (const float*)(buf + OFF_DEC);
;     bf16x8 Asc = {0, 0, 0, 0, 0, 0, 0, 0};
;     if (KS == 1 || wk == 0) {
;       f32x4 sc = {0.f, 0.f, 0.f, 0.f};
; #pragma unroll
;       for (int m = 0; m < DK / 32; ++m) {
;         const bf16x8 a = *(const bf16x8*)(ktil + r * QS + m * 32 + q4 * 8);
;         const bf16x8 bb = *(const bf16x8*)(qin + r * QS + m * 32 + q4 * 8);
;         sc = __builtin_amdgcn_mfma_f32_16x16x32_bf16(a, bb, sc, 0, 0, 0);
;       }
;       {
;         const unsigned p01 = pk2(q4 * 4 + 0 > r ? 0.f : sc[0], q4 * 4 + 1 > r ? 0.f : sc[1]);
;         const unsigned p23 = pk2(q4 * 4 + 2 > r ? 0.f : sc[2], q4 * 4 + 3 > r ? 0.f : sc[3]);
;         Asc[0] = (short)(p01 & 0xffff); Asc[1] = (short)(p01 >> 16); Asc[2] = (short)(p23 & 0xffff); Asc[3] = (short)(p23 >> 16);
;       }
;     }
;     bf16x8 Bv[NVT];
; #pragma unroll
;     for (int t = 0; t < NVT; ++t) {
;       const uint2 vv = *(const uint2*)(vT + ((vt0 + t) * 16 + r) * VS + q4 * 4);
;       Bv[t] = (bf16x8){(short)(vv.x & 0xffff), (short)(vv.x >> 16), (short)(vv.y & 0xffff), (short)(vv.y >> 16), 0, 0, 0, 0};
;     }
;     bf16x8 Aq[2];
; #pragma unroll
;     for (int m = 0; m < 2; ++m) {
;       const uint2 lo = *(const uint2*)(qin + r * QS + slab + (2 * m) * 16 + q4 * 4);
;       const uint2 hi = *(const uint2*)(qin + r * QS + slab + (2 * m + 1) * 16 + q4 * 4);
;       Aq[m] = (bf16x8){(short)(lo.x & 0xffff), (short)(lo.x >> 16), (short)(lo.y & 0xffff), (short)(lo.y >> 16),
;                        (short)(hi.x & 0xffff), (short)(hi.x >> 16), (short)(hi.y & 0xffff), (short)(hi.y >> 16)};
;     }
;     f32x4 o[NVT];
; #pragma unroll
;     for (int t = 0; t < NVT; ++t) {
;       o[t] = (f32x4){0.f, 0.f, 0.f, 0.f};
;       if (KS == 1 || wk == 0) o[t] = __builtin_amdgcn_mfma_f32_16x16x32_bf16(Asc, Bv[t], o[t], 0, 0, 0);
;     }
; #pragma unroll
;     for (int m = 0; m < 2; ++m)
; #pragma unroll
;       for (int t = 0; t < NVT; ++t) {
;         const f32x4 s0 = S[2 * m][t], s1 = S[2 * m + 1][t];
.Llw_join_647a:
	ds_read_b128 v[222:225], v46 offset:2304
	v_lshlrev_b32_e32 v208, 16, v55
	v_lshlrev_b32_e32 v192, 16, v59
	ds_read_b128 v[62:65], v46
	v_mul_f32_e32 v206, 0xbfb8aa3b, v208
	v_mul_f32_e32 v190, 0xbfb8aa3b, v192
	ds_read_b128 v[66:69], v46 offset:2368
	v_exp_f32_e32 v206, v206
	ds_read_b128 v[70:73], v46 offset:64
	v_exp_f32_e32 v190, v190
	v_and_b32_e32 v213, 0xffff0000, v55
	v_mov_b32_e32 v2, v3
	v_and_b32_e32 v195, 0xffff0000, v59
	v_mul_f32_e32 v207, 0xbfb8aa3b, v213
	v_add_u32_e32 v226, 0x2800, v53
	v_mul_f32_e32 v191, 0xbfb8aa3b, v195
	s_waitcnt lgkmcnt(2)
	v_mfma_f32_16x16x32_bf16 v[222:225], v[222:225], v[62:65], 0
	v_exp_f32_e32 v207, v207
	v_exp_f32_e32 v191, v191
	ds_read_b64 v[62:63], v47 offset:6656
	v_add_f32_e32 v206, 1.0, v206
	v_add_f32_e32 v190, 1.0, v190
	ds_read2_b64 v[74:77], v53 offset1:4
	v_rcp_f32_e32 v206, v206
	ds_read2_b64 v[78:81], v53 offset0:8 offset1:12
	v_rcp_f32_e32 v190, v190
	ds_write_b16 v42, v30 offset:30720
	v_mov_b32_e32 v64, v3
	v_mul_f32_e32 v192, 0x3fb8aa3b, v192
	ds_write_b16_d16_hi v42, v30 offset:30760
	v_mov_b32_e32 v65, v3
	v_add_f32_e32 v191, 1.0, v191
	s_waitcnt lgkmcnt(5)
	v_mfma_f32_16x16x32_bf16 v[222:225], v[66:69], v[70:73], v[222:225]
	v_add_f32_e32 v207, 1.0, v207
	v_rcp_f32_e32 v191, v191
	s_waitcnt lgkmcnt(3)
	v_bfi_b32 v76, s30, v76, v76
	v_rcp_f32_e32 v207, v207
	v_fma_f32 v190, v24, v190, v20
	s_waitcnt lgkmcnt(2)
	v_bfi_b32 v80, s30, v80, v80
	v_fma_f32 v206, v24, v206, v20
	v_cvt_pk_bf16_f32 v66, v16, v17
	v_max_f32_e32 v206, 0x1e3ce508, v206
	v_max_f32_e32 v190, 0x1e3ce508, v190
	v_cvt_pk_bf16_f32 v67, v18, v19
	v_cmp_gt_f32_e64 s[36:37], s26, v206
	v_cvt_pk_bf16_f32 v68, v12, v13
	v_cmp_gt_f32_e32 vcc, s26, v190
	v_fma_f32 v207, v25, v207, v21
	v_cndmask_b32_e64 v0, v222, 0, s[6:7]
	v_fma_f32 v191, v25, v191, v21
	v_max_f32_e32 v207, 0x1e3ce508, v207
	v_cndmask_b32_e64 v1, 0, v223, s[8:9]
	v_max_f32_e32 v191, 0x1e3ce508, v191
	v_cndmask_b32_e64 v222, v224, 0, s[10:11]
	v_cndmask_b32_e64 v210, 0, 32, s[36:37]
	v_cndmask_b32_e64 v196, 0, 32, vcc
	v_cndmask_b32_e64 v223, v225, 0, s[12:13]
	v_ldexp_f32 v206, v206, v210
	v_ldexp_f32 v190, v190, v196
	v_cvt_pk_bf16_f32 v0, v0, v1
	v_log_f32_e32 v206, v206
	v_cvt_pk_bf16_f32 v1, v222, v223
	v_log_f32_e32 v190, v190
	v_cmp_gt_f32_e64 s[38:39], s26, v207
	v_cvt_pk_bf16_f32 v69, v14, v15
	v_cmp_gt_f32_e64 s[16:17], s26, v191
	ds_write_b16 v42, v31 offset:30800
	v_mfma_f32_16x16x32_bf16 v[222:225], v[0:3], v[62:65], 0
	v_exp_f32_e32 v192, v192
	v_mfma_f32_16x16x32_bf16 v[222:225], v[74:77], v[66:69], v[222:225]
	ds_write_b16_d16_hi v42, v31 offset:30840
	v_mul_f32_e32 v195, 0x3fb8aa3b, v195
	v_cvt_pk_bf16_f32 v66, v8, v9
	v_cndmask_b32_e64 v211, 0, 32, s[38:39]
	v_cndmask_b32_e64 v196, 0, 32, s[16:17]
	v_cvt_pk_bf16_f32 v67, v10, v11
	v_mul_f32_e32 v210, 0x3f317217, v206
	v_cvt_pk_bf16_f32 v68, v4, v5
	v_mul_f32_e32 v197, 0x3f317217, v190
	v_ldexp_f32 v207, v207, v211
	v_cvt_pk_bf16_f32 v69, v6, v7
	v_fma_f32 v210, v206, s31, -v210
	v_ldexp_f32 v191, v191, v196
	v_mfma_f32_16x16x32_bf16 v[222:225], v[78:81], v[66:69], v[222:225]
	v_log_f32_e32 v207, v207
	s_nop 6
	v_cvt_pk_bf16_f32 v0, v222, s0
	v_fma_f32 v197, v190, s31, -v197
	v_fmac_f32_e32 v210, 0x3377d1cf, v206
	v_cvt_pk_bf16_f32 v1, v223, s0
	v_log_f32_e32 v191, v191
	ds_write_b16 v48, v0 offset:48128
	v_fmac_f32_e32 v210, 0x3f317217, v206
	v_fmac_f32_e32 v197, 0x3377d1cf, v190
	ds_write_b16 v48, v1 offset:48392
	v_cmp_lt_f32_e64 s[40:41], |v206|, s27
	v_fmac_f32_e32 v197, 0x3f317217, v190
	v_cvt_pk_bf16_f32 v0, v224, s0
	v_mul_f32_e32 v208, 0x3fb8aa3b, v208
	ds_write_b16 v48, v0 offset:48656
	v_cmp_lt_f32_e64 s[18:19], |v190|, s27
	v_exp_f32_e32 v208, v208
	v_cvt_pk_bf16_f32 v0, v225, s0
	v_cndmask_b32_e32 v196, 0, v157, vcc
	v_cndmask_b32_e64 v206, v206, v210, s[40:41]
	ds_write_b16 v48, v0 offset:48920
	v_exp_f32_e32 v195, v195
	ds_read2st64_b64 v[222:225], v49 offset0:9 offset1:10
	v_cndmask_b32_e64 v210, 0, v157, s[36:37]
	v_cndmask_b32_e64 v190, v190, v197, s[18:19]
	ds_read2st64_b64 v[66:69], v49 offset0:11 offset1:12
	v_sub_f32_e32 v206, v206, v210
	v_sub_f32_e32 v190, v190, v196
	ds_read_b128 v[70:73], v50 offset:11776
	v_mul_f32_e32 v210, 0x3f317217, v207
	ds_read_b128 v[74:77], v50 offset:11840
	v_mul_f32_e32 v196, 0x3f317217, v191
	v_mul_f32_e32 v211, 0x3fb8aa3b, v213
	s_waitcnt lgkmcnt(1)
	v_pk_mul_f32 v[18:19], v[18:19], v[72:73]
	v_fma_f32 v196, v191, s31, -v196
	v_fma_f32 v210, v207, s31, -v210
	v_pk_mul_f32 v[16:17], v[16:17], v[70:71]
	v_exp_f32_e32 v213, v211
	s_waitcnt lgkmcnt(0)
	v_pk_mul_f32 v[14:15], v[14:15], v[76:77]
	v_fmac_f32_e32 v196, 0x3377d1cf, v191
	v_fmac_f32_e32 v210, 0x3377d1cf, v207
	v_pk_mul_f32 v[12:13], v[12:13], v[74:75]
	v_fmac_f32_e32 v196, 0x3f317217, v191
	v_fmac_f32_e32 v210, 0x3f317217, v207
	v_mfma_f32_16x16x16_bf16 v[16:19], v[222:223], v[62:63], v[16:19]
	v_cmp_lt_f32_e64 vcc, |v191|, s27
	v_mov_b32_e32 v0, v224
	v_cmp_lt_f32_e64 s[36:37], |v207|, s27
	v_add_f32_e32 v192, 1.0, v192
	v_mov_b32_e32 v1, v225
	v_add_f32_e32 v208, 1.0, v208
	ds_read_b128 v[222:225], v50 offset:11904
	v_rcp_f32_e32 v198, v192
	v_and_b32_e32 v211, 0xffff0000, v54
	ds_read_b128 v[70:73], v50 offset:11968
	v_cndmask_b32_e32 v191, v191, v196, vcc
	v_cndmask_b32_e64 v207, v207, v210, s[36:37]
	v_mfma_f32_16x16x16_bf16 v[12:15], v[0:1], v[62:63], v[12:15]
	v_cndmask_b32_e64 v196, 0, v157, s[16:17]
	s_waitcnt lgkmcnt(1)
; template <int MODE>
; __device__ void scan_unit(int swave, const Params& p, int j, int b, int h, int dir, char* shm) {
;     ...
;   auto compute = [&](const char* buf, bf16_t* obuf) {
;     const bf16_t* qin = (const bf16_t*)buf; const bf16_t* ktil = (const bf16_t*)(buf + OFF_KT); const bf16_t* koutT = (const bf16_t*)(buf + OFF_KO);
;     const bf16_t* vT = (const bf16_t*)(buf + OFF_VT); const float* dec = (const float*)(buf + OFF_DEC);
;     bf16x8 Asc = {0, 0, 0, 0, 0, 0, 0, 0};
;     if (KS == 1 || wk == 0) {
;       f32x4 sc = {0.f, 0.f, 0.f, 0.f};
; #pragma unroll
;       for (int m = 0; m < DK / 32; ++m) {
;         const bf16x8 a = *(const bf16x8*)(ktil + r * QS + m * 32 + q4 * 8);
;         const bf16x8 bb = *(const bf16x8*)(qin + r * QS + m * 32 + q4 * 8);
;         sc = __builtin_amdgcn_mfma_f32_16x16x32_bf16(a, bb, sc, 0, 0, 0);
;       }
;       {
;         const unsigned p01 = pk2(q4 * 4 + 0 > r ? 0.f : sc[0], q4 * 4 + 1 > r ? 0.f : sc[1]);
;         const unsigned p23 = pk2(q4 * 4 + 2 > r ? 0.f : sc[2], q4 * 4 + 3 > r ? 0.f : sc[3]);
;         Asc[0] = (short)(p01 & 0xffff); Asc[1] = (short)(p01 >> 16); Asc[2] = (short)(p23 & 0xffff); Asc[3] = (short)(p23 >> 16);
;       }
;     }
;     bf16x8 Bv[NVT];
; #pragma unroll
;     for (int t = 0; t < NVT; ++t) {
;       const uint2 vv = *(const uint2*)(vT + ((vt0 + t) * 16 + r) * VS + q4 * 4);
;       Bv[t] = (bf16x8){(short)(vv.x & 0xffff), (short)(vv.x >> 16), (short)(vv.y & 0xffff), (short)(vv.y >> 16), 0, 0, 0, 0};
;     }
;     bf16x8 Aq[2];
; #pragma unroll
;     for (int m = 0; m < 2; ++m) {
;       const uint2 lo = *(const uint2*)(qin + r * QS + slab + (2 * m) * 16 + q4 * 4);
;       const uint2 hi = *(const uint2*)(qin + r * QS + slab + (2 * m + 1) * 16 + q4 * 4);
;       Aq[m] = (bf16x8){(short)(lo.x & 0xffff), (short)(lo.x >> 16), (short)(lo.y & 0xffff), (short)(lo.y >> 16),
;                        (short)(hi.x & 0xffff), (short)(hi.x >> 16), (short)(hi.y & 0xffff), (short)(hi.y >> 16)};
;     }
;     f32x4 o[NVT];
; #pragma unroll
;     for (int t = 0; t < NVT; ++t) {
;       o[t] = (f32x4){0.f, 0.f, 0.f, 0.f};
;       if (KS == 1 || wk == 0) o[t] = __builtin_amdgcn_mfma_f32_16x16x32_bf16(Asc, Bv[t], o[t], 0, 0, 0);
;     }
; #pragma unroll
;     for (int m = 0; m < 2; ++m)
; #pragma unroll
;       for (int t = 0; t < NVT; ++t) {
;         const f32x4 s0 = S[2 * m][t], s1 = S[2 * m + 1][t];
	v_pk_mul_f32 v[10:11], v[10:11], v[224:225]
	v_cndmask_b32_e64 v210, 0, v157, s[38:39]
	v_sub_f32_e32 v191, v191, v196
	v_pk_mul_f32 v[8:9], v[8:9], v[222:223]
	v_sub_f32_e32 v207, v207, v210
	v_lshlrev_b32_e32 v196, 16, v57
	v_cvt_pk_bf16_f32 v74, v16, v17
	v_lshlrev_b32_e32 v210, 16, v54
	v_cvt_pk_bf16_f32 v75, v18, v19
	v_add_f32_e32 v192, 1.0, v195
	v_rcp_f32_e32 v212, v208
	v_mfma_f32_16x16x16_bf16 v[222:225], v[66:67], v[62:63], v[8:11]
	v_and_b32_e32 v197, 0xffff0000, v57
	v_add_f32_e32 v208, 1.0, v213
	v_cvt_pk_bf16_f32 v76, v12, v13
	v_rcp_f32_e32 v213, v208
	ds_read_b128 v[8:11], v46 offset:14336
	v_rcp_f32_e32 v199, v192
	v_mul_f32_e32 v208, 0xbfb8aa3b, v210
	s_waitcnt lgkmcnt(1)
	v_pk_mul_f32 v[6:7], v[6:7], v[72:73]
	v_mul_f32_e32 v192, 0xbfb8aa3b, v196
	v_exp_f32_e32 v208, v208
	v_pk_mul_f32 v[4:5], v[4:5], v[70:71]
	v_exp_f32_e32 v192, v192
	v_cvt_pk_bf16_f32 v77, v14, v15
	v_mul_f32_e32 v218, 0xbfb8aa3b, v211
	v_mul_f32_e32 v193, 0xbfb8aa3b, v197
	v_mfma_f32_16x16x16_bf16 v[4:7], v[68:69], v[62:63], v[4:7]
	v_exp_f32_e32 v219, v218
	v_exp_f32_e32 v193, v193
	ds_read_b128 v[62:65], v46 offset:14400
	v_add_f32_dpp v206, v206, v206 row_shr:1 row_mask:0xf bank_mask:0xf bound_ctrl:1
	ds_read_b128 v[66:69], v46 offset:12032
	v_add_f32_dpp v190, v190, v190 row_shr:1 row_mask:0xf bank_mask:0xf bound_ctrl:1
	v_add_f32_dpp v207, v207, v207 row_shr:1 row_mask:0xf bank_mask:0xf bound_ctrl:1
	ds_read_b128 v[70:73], v46 offset:12096
	v_add_f32_dpp v191, v191, v191 row_shr:1 row_mask:0xf bank_mask:0xf bound_ctrl:1
	s_waitcnt lgkmcnt(1)
	v_mfma_f32_16x16x32_bf16 v[8:11], v[8:11], v[66:69], 0
	v_add_f32_e32 v208, 1.0, v208
	v_add_f32_e32 v192, 1.0, v192
	v_mov_b32_e32 v68, v3
	v_add_f32_dpp v206, v206, v206 row_shr:2 row_mask:0xf bank_mask:0xf bound_ctrl:1
	v_add_f32_dpp v190, v190, v190 row_shr:2 row_mask:0xf bank_mask:0xf bound_ctrl:1
	v_mov_b32_e32 v69, v3
	v_add_f32_dpp v207, v207, v207 row_shr:2 row_mask:0xf bank_mask:0xf bound_ctrl:1
	s_waitcnt lgkmcnt(0)
	v_mfma_f32_16x16x32_bf16 v[8:11], v[62:65], v[70:73], v[8:11]
	v_add_f32_dpp v191, v191, v191 row_shr:2 row_mask:0xf bank_mask:0xf bound_ctrl:1
	v_rcp_f32_e32 v218, v208
	s_nop 5
	v_cndmask_b32_e64 v0, v8, 0, s[6:7]
	v_rcp_f32_e32 v200, v192
	v_add_f32_e32 v208, 1.0, v219
	v_cndmask_b32_e64 v1, 0, v9, s[8:9]
	v_add_f32_e32 v192, 1.0, v193
	v_cvt_pk_bf16_f32 v0, v0, v1
	v_add_f32_dpp v206, v206, v206 row_shr:4 row_mask:0xf bank_mask:0xf bound_ctrl:1
	v_add_f32_dpp v207, v207, v207 row_shr:4 row_mask:0xf bank_mask:0xf bound_ctrl:1
	v_cndmask_b32_e64 v1, v10, 0, s[10:11]
	v_add_f32_dpp v190, v190, v190 row_shr:4 row_mask:0xf bank_mask:0xf bound_ctrl:1
	v_rcp_f32_e32 v219, v208
	v_cndmask_b32_e64 v2, v11, 0, s[12:13]
	v_add_f32_dpp v191, v191, v191 row_shr:4 row_mask:0xf bank_mask:0xf bound_ctrl:1
	ds_read2_b64 v[8:11], v226 offset0:224 offset1:228
	v_add_f32_dpp v215, v206, v206 row_shr:8 row_mask:0xf bank_mask:0xf bound_ctrl:1
	v_rcp_f32_e32 v201, v192
	ds_read2_b64 v[62:65], v226 offset0:232 offset1:236
	v_add_f32_dpp v217, v207, v207 row_shr:8 row_mask:0xf bank_mask:0xf bound_ctrl:1
	v_add_f32_dpp v204, v190, v190 row_shr:8 row_mask:0xf bank_mask:0xf bound_ctrl:1
	v_cvt_pk_bf16_f32 v1, v1, v2
	v_mul_f32_e32 v220, 0x3fb8aa3b, v215
	ds_read_b64 v[66:67], v47 offset:18688
	v_add_f32_dpp v205, v191, v191 row_shr:8 row_mask:0xf bank_mask:0xf bound_ctrl:1
	v_mul_f32_e32 v208, 0x3fb8aa3b, v217
	v_mov_b32_e32 v2, v3
	v_mul_f32_e32 v195, 0x3fb8aa3b, v204
	v_exp_f32_e32 v220, v220
	s_waitcnt lgkmcnt(2)
	v_bfi_b32 v10, s30, v10, v10
	v_mul_f32_e32 v192, 0x3fb8aa3b, v205
	s_waitcnt lgkmcnt(1)
	v_bfi_b32 v64, s30, v64, v64
	v_exp_f32_e32 v221, v208
	v_exp_f32_e32 v202, v195
	s_waitcnt lgkmcnt(0)
	v_mfma_f32_16x16x32_bf16 v[70:73], v[0:3], v[66:69], 0
	v_mul_f32_e32 v208, 0xbfb8aa3b, v215
	v_mfma_f32_16x16x32_bf16 v[8:11], v[8:11], v[74:77], v[70:73]
	v_exp_f32_e32 v203, v192
	v_pk_mul_f32 v[210:211], v[218:219], v[210:211]
	s_nop 3
	v_cvt_pk_bf16_f32 v70, v222, v223
	v_mul_f32_e32 v192, 0xbfb8aa3b, v204
	v_exp_f32_e32 v218, v208
	v_cvt_pk_bf16_f32 v71, v224, v225
	v_pk_mul_f32 v[196:197], v[200:201], v[196:197]
	v_cvt_pk_bf16_f32 v72, v4, v5
	v_mul_f32_e32 v208, 0xbfb8aa3b, v217
	v_exp_f32_e32 v200, v192
	v_cvt_pk_bf16_f32 v73, v6, v7
	v_exp_f32_e32 v219, v208
	ds_bpermute_b32 v206, v38, v215
	v_mfma_f32_16x16x32_bf16 v[8:11], v[62:65], v[70:73], v[8:11]
	v_mul_f32_e32 v192, 0xbfb8aa3b, v205
	v_add_u32_e32 v62, 0x100, v49
	v_pk_mul_f32 v[210:211], v[210:211], v[220:221]
	v_exp_f32_e32 v201, v192
	s_nop 3
	v_cvt_pk_bf16_f32 v0, v8, s0
	ds_bpermute_b32 v207, v38, v217
	ds_bpermute_b32 v190, v38, v204
	ds_write_b16 v48, v0 offset:52352
	v_cvt_pk_bf16_f32 v208, v210, v211
	v_cvt_pk_bf16_f32 v0, v9, s0
	v_pk_mul_f32 v[196:197], v[196:197], v[202:203]
	v_pk_mul_f32 v[210:211], v[24:25], v[212:213]
	ds_write_b16 v48, v0 offset:52616
	ds_bpermute_b32 v191, v38, v205
	v_pk_mul_f32 v[212:213], v[210:211], v[218:219]
	v_cvt_pk_bf16_f32 v0, v10, s0
	v_cvt_pk_bf16_f32 v192, v196, v197
	ds_write_b16 v48, v0 offset:52880
	v_cvt_pk_bf16_f32 v212, v212, v213
	v_pk_mul_f32 v[196:197], v[24:25], v[198:199]
	v_cvt_pk_bf16_f32 v0, v11, s0
	ds_write2st64_b32 v39, v208, v212 offset0:141 offset1:150
	v_pk_mul_f32 v[198:199], v[196:197], v[200:201]
	ds_write_b16 v48, v0 offset:53144
	s_waitcnt lgkmcnt(8)
	v_sub_f32_e32 v208, v206, v215
	ds_read2st64_b64 v[70:73], v62 offset0:32 offset1:33
	v_cvt_pk_bf16_f32 v193, v198, v199
	v_mul_f32_e32 v208, 0x3fb8aa3b, v208
	ds_read2st64_b64 v[74:77], v62 offset0:34 offset1:35
	ds_write2st64_b32 v39, v192, v193 offset0:94 offset1:103
	ds_read_b128 v[8:11], v50 offset:23808
	v_exp_f32_e32 v208, v208
	s_waitcnt lgkmcnt(10)
	v_sub_f32_e32 v192, v190, v204
	ds_read_b128 v[78:81], v50 offset:23872
	v_sub_f32_e32 v212, v207, v217
	v_mul_f32_e32 v192, 0x3fb8aa3b, v192
	s_waitcnt lgkmcnt(1)
	v_pk_mul_f32 v[10:11], v[18:19], v[10:11]
	v_mul_f32_e32 v212, 0x3fb8aa3b, v212
	v_pk_mul_f32 v[8:9], v[16:17], v[8:9]
	v_exp_f32_e32 v212, v212
	v_exp_f32_e32 v192, v192
	s_waitcnt lgkmcnt(0)
	v_pk_mul_f32 v[14:15], v[14:15], v[80:81]
	v_mul_f32_e32 v208, v210, v208
	v_sub_f32_e32 v193, v191, v205
	v_pk_mul_f32 v[12:13], v[12:13], v[78:79]
	v_cvt_pk_bf16_f32 v208, v208, s0
	v_mfma_f32_16x16x16_bf16 v[8:11], v[70:71], v[66:67], v[8:11]
	v_mul_f32_e32 v193, 0x3fb8aa3b, v193
	ds_write_b16 v40, v208 offset:40704
	v_mov_b32_e32 v0, v72
	v_exp_f32_e32 v193, v193
	v_mul_f32_e32 v208, v211, v212
	v_mov_b32_e32 v1, v73
	v_mul_f32_e32 v192, v196, v192
	ds_read_b128 v[16:19], v50 offset:23936
	v_cvt_pk_bf16_f32 v208, v208, s0
	v_cvt_pk_bf16_f32 v192, v192, s0
	ds_read_b128 v[70:73], v50 offset:24000
	ds_write_b16 v40, v208 offset:40736
	ds_write_b16 v40, v192 offset:28672
	v_mfma_f32_16x16x16_bf16 v[12:15], v[0:1], v[66:67], v[12:15]
	s_and_saveexec_b64 s[38:39], s[14:15]
	s_cbranch_execz .LBB0_656
	v_mul_f32_e32 v207, 0x3fb8aa3b, v207
	v_mul_f32_e32 v206, 0x3fb8aa3b, v206
	v_exp_f32_e32 v207, v207
	v_exp_f32_e32 v206, v206
	ds_write_b64 v41, v[206:207] offset:47872
; __device__ __forceinline__ unsigned pk2(float lo, float hi) { f32x2_t v = {lo, hi}; bf16x2_t b = __builtin_convertvector(v, bf16x2_t); return __builtin_bit_cast(unsigned, b); }
; __device__ __forceinline__ bf16_t f2bf(float f) { return (bf16_t)(pk2(f, 0.f) & 0xffffu); }
; template <int MODE>
; __device__ void scan_unit(int swave, const Params& p, int j, int b, int h, int dir, char* shm) {
;     ...
;       *(unsigned*)(qin + ti * QS + dp) = pk2(q0 * __expf(cum0), q1 * __expf(cum1));
;       *(unsigned*)(ktil + ti * QS + dp) = pk2(k0 * __expf(-cum0), k1 * __expf(-cum1));
;       koutT[dp * 16 + ti] = f2bf(k0 * __expf(s0 - cum0));
;       koutT[(dp + 1) * 16 + ti] = f2bf(k1 * __expf(s1 - cum1));
;       if (ti == 0) *(float2*)(dec + dp) = make_float2(__expf(s0), __expf(s1));
;       const unsigned v0 = R.v.x, v1 = R.v.y; const int c4 = vg * 4;
;       vT[(c4 + 0) * VS + ti] = (bf16_t)(v0 & 0xffff); vT[(c4 + 1) * VS + ti] = (bf16_t)(v0 >> 16);
;       vT[(c4 + 2) * VS + ti] = (bf16_t)(v1 & 0xffff); vT[(c4 + 3) * VS + ti] = (bf16_t)(v1 >> 16);
;     ...
;       for (int jj = 0; jj < 4; ++jj) obuf[(wk * 16 + q4 * 4 + jj) * OS + (vt0 + t) * 16 + r] = f2bf(o[t][jj]);
; #pragma unroll
;     for (int kt = 0; kt < 4; ++kt) {
;       const uint2 kk = *(const uint2*)(koutT + (slab + kt * 16 + r) * 16 + q4 * 4);
;       const bf16x8 Ak = {(short)(kk.x & 0xffff), (short)(kk.x >> 16), (short)(kk.y & 0xffff), (short)(kk.y >> 16), 0, 0, 0, 0};
;       const f32x4 dc = *(const f32x4*)(dec + slab + kt * 16 + q4 * 4);
; #pragma unroll
;       for (int t = 0; t < NVT; ++t) S[kt][t] = __builtin_amdgcn_mfma_f32_16x16x32_bf16(Ak, Bv[t], S[kt][t] * dc, 0, 0, 0);
;     }
.LBB0_656:
	s_or_b64 exec, exec, s[38:39]
	s_waitcnt lgkmcnt(3)
	v_pk_mul_f32 v[18:19], v[224:225], v[18:19]
	v_mul_f32_e32 v192, v197, v193
	ds_write_b16 v42, v28 offset:42752
	v_pk_mul_f32 v[16:17], v[222:223], v[16:17]
	v_cvt_pk_bf16_f32 v192, v192, s0
	ds_write_b16_d16_hi v42, v28 offset:42792
	s_waitcnt lgkmcnt(4)
	v_pk_mul_f32 v[6:7], v[6:7], v[72:73]
	ds_write_b16 v40, v192 offset:28704
	v_pk_mul_f32 v[4:5], v[4:5], v[70:71]
	ds_write_b16 v42, v29 offset:42832
	s_and_saveexec_b64 s[16:17], s[14:15]
	s_cbranch_execz .LBB0_654
	v_mul_f32_e32 v191, 0x3fb8aa3b, v191
	v_mul_f32_e32 v190, 0x3fb8aa3b, v190
	v_exp_f32_e32 v191, v191
	v_exp_f32_e32 v190, v190
	ds_write_b64 v41, v[190:191] offset:35840
.LBB0_654:
	s_or_b64 exec, exec, s[16:17]
	v_mfma_f32_16x16x16_bf16 v[16:19], v[74:75], v[66:67], v[16:19]
	ds_write_b16_d16_hi v42, v29 offset:42872
	s_waitcnt lgkmcnt(0)
	s_barrier
	v_mfma_f32_16x16x16_bf16 v[4:7], v[76:77], v[66:67], v[4:7]
	s_add_i32 s16, s20, 0x60
	s_and_b64 s[2:3], s[2:3], exec
	s_cselect_b32 s2, s16, 0x7e0
	v_or_b32_e32 v2, s2, v37
	v_sub_u32_e32 v0, 0x7ff, v2
	v_cndmask_b32_e64 v0, v0, v2, s[0:1]
	v_or_b32_e32 v2, 16, v2
	v_ashrrev_i32_e32 v1, 31, v0
	v_sub_u32_e32 v57, 0x7ff, v2
	v_lshl_add_u64 v[0:1], s[46:47], 0, v[0:1]
	v_mov_b64_e32 v[28:29], s[48:49]
	v_cndmask_b32_e64 v64, v57, v2, s[0:1]
	v_mad_u64_u32 v[30:31], s[2:3], v0, s53, v[28:29]
	v_ashrrev_i32_e32 v65, 31, v64
	v_mad_i32_i24 v31, v1, s53, v31
	s_mov_b32 s71, s95
	v_lshl_add_u64 v[64:65], s[46:47], 0, v[64:65]
	v_lshl_add_u64 v[0:1], v[30:31], 0, s[50:51]
	v_lshl_add_u64 v[54:55], v[30:31], 0, s[94:95]
	v_lshl_add_u64 v[30:31], v[30:31], 0, s[70:71]
	v_mad_u64_u32 v[28:29], s[2:3], v64, s53, v[28:29]
	v_lshl_add_u64 v[30:31], v[30:31], 0, v[26:27]
	v_mad_i32_i24 v29, v65, s53, v29
	v_lshl_add_u64 v[54:55], v[54:55], 0, s[50:51]
	v_add_co_u32_e32 v30, vcc, s62, v30
	v_lshl_add_u64 v[66:67], v[28:29], 0, s[94:95]
	v_lshl_add_u64 v[0:1], v[0:1], 0, v[22:23]
	v_lshl_add_u64 v[54:55], v[54:55], 0, v[22:23]
	v_addc_co_u32_e32 v31, vcc, 0, v31, vcc
	v_lshl_add_u64 v[64:65], v[28:29], 0, s[50:51]
	v_lshl_add_u64 v[66:67], v[66:67], 0, s[50:51]
	v_lshl_add_u64 v[64:65], v[64:65], 0, v[22:23]
	v_lshl_add_u64 v[66:67], v[66:67], 0, v[22:23]
	global_load_dword v57, v[0:1], off offset:3136
	global_load_dword v59, v[54:55], off
	s_nop 0
	global_load_dwordx2 v[30:31], v[30:31], off offset:576
	s_nop 0
	global_load_dword v54, v[64:65], off offset:3136
	global_load_dword v55, v[66:67], off
	v_lshl_add_u64 v[0:1], v[28:29], 0, s[70:71]
	v_lshl_add_u64 v[0:1], v[0:1], 0, v[26:27]
	v_add_co_u32_e32 v0, vcc, 0x1000, v0
	s_nop 1
	v_addc_co_u32_e32 v1, vcc, 0, v1, vcc
	global_load_dwordx2 v[28:29], v[0:1], off offset:576
	s_and_saveexec_b64 s[2:3], s[4:5]
	s_cbranch_execz .LBB0_661
	s_sub_i32 vcc_lo, 0x7e0, s20
	s_cmp_lg_u64 s[0:1], 0
	s_cselect_b32 vcc_lo, s20, vcc_lo
	s_add_i32 vcc_lo, vcc_lo, s46
	s_lshl_b32 vcc_lo, vcc_lo, 11
	s_add_u32 s16, s68, vcc_lo
	s_addc_u32 s17, s69, 0
	v_add_u32_e32 v160, v51, v166
	v_add_u32_e32 v161, v52, v166
	ds_read_b64 v[162:163], v160
	ds_read_b64 v[164:165], v161
	s_waitcnt lgkmcnt(1)
	global_store_dwordx2 v167, v[162:163], s[16:17]
	s_waitcnt lgkmcnt(0)
	global_store_dwordx2 v168, v[164:165], s[16:17]
	s_or_b64 exec, exec, s[2:3]
	s_waitcnt vmcnt(8)
	s_branch .Llw_join_647b
